# light in-proj workgroups delayed ~24 us instead of ~16 us (run 1)
# baseline (speedup 1.0000x reference)
; #define GAS __attribute__((address_space(1)))
;     __device__ __forceinline__ GAS float* outp() const { return (GAS float*)rd(17); }
;     __device__ __forceinline__ GAS unsigned char* wsp() const { return (GAS unsigned char*)rd(18); }
; #define F_qng F.in(9)
; __global__ void __launch_bounds__(512, 2) mega_fwd(Params p) {
;     ...
;         if (IN(pb + 1)) { pg8::Gemm g{(const GAS bf16*)(F.wsp() + WS_XN), (const GAS bf16*)(F.wsp() + WS_WIN) + (size_t)l * NPROJ * D, 0, 0, MTOT / 256, NPROJ / 256, 1, D, 0, WGM_PROJ};
;             pg8::Order S; S.init(g, F.G, (int)blockIdx.x);
;             pg8::EpiProj E{l, F.wsp(), F.outp(), F_qng + l * 128, F_kng + l * 128, (const GAS float*)(F.wsp() + WS_LB) + l * 1024};
;             pg8::gemm_phase(F.lds, g, S, E, F.wave);
.LBB0_172:
	s_cmpk_lt_u32 s101, 0xd4
	s_cbranch_scc1 .Lip_nodelay
	s_movk_i32 s100, 6
